# attention: per-lane partial row-sum l (cross-half combine deferred to block end), mask row index derived from s33 in the mask block
# baseline (speedup 1.0000x reference)
; #define WAIT_BAR(N) do { if constexpr (VAR & 4) asm volatile("s_waitcnt vmcnt(" #N ") lgkmcnt(0)" ::: "memory"); else asm volatile("s_waitcnt vmcnt(" #N ") lgkmcnt(0)\n\ts_barrier" ::: "memory"); } while (0)
; #define DMA_K(t, slot) do { if constexpr ((VAR & 16) != 0) break; __builtin_amdgcn_global_load_lds((const unsigned*)(ksrc + (size_t)TT(t) * 64 * KVW), (LAS unsigned*)(kdst + (slot) * KSLOT), 16, 0, 0); \
;                             __builtin_amdgcn_global_load_lds((const unsigned*)(rsrc + (size_t)TT(t) * 64 * ROPE), (LAS unsigned*)(rdst + (slot) * KSLOT), 16, 0, 0); } while (0)
; #define DMA_V(t, slot) do { if constexpr ((VAR & 16) == 0) __builtin_amdgcn_global_load_lds((const unsigned*)(vsrc + (size_t)TT(t) * 64 * KVW), (LAS unsigned*)(vdst + (slot) * VSLOT), 16, 0, 0); } while (0)
; #define KLOAD(slot) do { const LAS unsigned char* kb_ = kb0 + (slot) * KSLOT; _Pragma("unroll") for (int d0 = 0; d0 < 6; ++d0) { kf[2 * d0] = *(const LAS bf16x8*)(kb_ + d0 * 512); kf[2 * d0 + 1] = *(const LAS bf16x8*)(kb_ + d0 * 512 + 6144); } } while (0)
; #define MASKT(P0_, P1_, t) do { const int kbm_ = TT(t) * 64; if (kbm_ + 63 > qlo) mask_tile(P0_, P1_, qm - kbm_); } while (0)
; #define SHIFT(P0_, P1_, dl_) do { m_reg += (dl_); _Pragma("unroll") for (int r = 0; r < 16; ++r) { P0_[r] -= (dl_); P1_[r] -= (dl_); } _Pragma("unroll") for (int r = 0; r < 16; ++r) negm[r] = -m_reg; } while (0)
; #define PBAR_V(t) do { if ((t) + 3 < NT) { WAIT_BAR(6); } else { WAIT_BAR(0); } } while (0)
; template <int VAR> __device__ __forceinline__ void block(const bf16* Q, const bf16* KVB, const bf16* KR, const float* cosT, bf16* OB, LAS unsigned char* lds, int b, int h, int qb, int t0, int wv, ...
;     ...
;     if (trail) WAIT_BAR(0);
;     DMA_K(3, 3); DMA_V(2, 2);
;     KLOAD(0); QK(px0, px1);
;     PBAR_V(0);
;     MASKT(px0, px1, 0);
;     { float pm; ROWMAX(px0, px1, pm); SHIFT(px0, px1, pm); TILE_VALU(1.f); pa0 = pn0; pa1 = pn1; pa2 = pn2; pa3 = pn3; }
;     int sk = 1, sv = 0;
.LBB0_1407:
	v_lshrrev_b32_e32 v33, 2, v152
	v_lshlrev_b32_e32 v32, 5, v59
	v_or_b32_e32 v33, v166, v33
	s_add_i32 s2, 0, 0xc000
	v_and_b32_e32 v32, 32, v32
	v_lshlrev_b32_e32 v33, 6, v33
	v_add_u32_e32 v34, s2, v61
	v_add3_u32 v172, v34, v32, v33
	s_nop 2
	v_max_f32_e32 v32, v16, v16
	v_max_f32_e32 v33, v0, v0
	v_max_f32_e32 v32, v33, v32
	v_max_f32_e32 v33, v17, v17
	v_max_f32_e32 v34, v1, v1
	v_max_f32_e32 v33, v34, v33
	v_max_f32_e32 v34, v19, v19
	v_max_f32_e32 v35, v3, v3
	v_max_f32_e32 v34, v35, v34
	v_max3_f32 v35, v2, v18, v6
	v_max3_f32 v34, v34, v7, v23
	v_max3_f32 v32, v32, v4, v20
	v_max3_f32 v33, v33, v5, v21
	v_max3_f32 v35, v35, v22, v10
	v_max3_f32 v34, v34, v11, v27
	v_max3_f32 v32, v32, v8, v24
	v_max3_f32 v33, v33, v9, v25
	v_max3_f32 v35, v35, v26, v14
	v_max3_f32 v34, v34, v15, v31
	v_max3_f32 v32, v32, v12, v28
	v_max3_f32 v33, v33, v13, v29
	v_max3_f32 v34, v35, v30, v34
	v_max3_f32 v32, v32, v33, v34
	v_mov_b32_e32 v33, v32
	s_nop 1
	v_permlane32_swap_b32_e32 v32, v33
	v_max_f32_e32 v33, v33, v33
	v_max_f32_e32 v32, v32, v32
	v_max_f32_e32 v33, v32, v33
	v_sub_f32_e32 v0, v0, v33
	v_sub_f32_e32 v16, v16, v33
	v_sub_f32_e32 v34, v17, v33
	v_sub_f32_e32 v2, v2, v33
	v_sub_f32_e32 v18, v18, v33
	v_sub_f32_e32 v17, v3, v33
	v_sub_f32_e32 v35, v19, v33
	v_sub_f32_e32 v19, v4, v33
	v_sub_f32_e32 v36, v20, v33
	v_sub_f32_e32 v20, v5, v33
	v_sub_f32_e32 v37, v21, v33
	v_sub_f32_e32 v6, v6, v33
	v_sub_f32_e32 v22, v22, v33
	v_sub_f32_e32 v21, v7, v33
	v_sub_f32_e32 v32, v1, v33
	v_sub_f32_e32 v38, v23, v33
	v_sub_f32_e32 v23, v9, v33
	v_exp_f32_e32 v1, v0
	v_exp_f32_e32 v4, v2
	v_exp_f32_e32 v2, v17
	v_exp_f32_e32 v5, v19
	v_exp_f32_e32 v7, v20
	v_exp_f32_e32 v0, v6
	v_exp_f32_e32 v6, v21
	v_exp_f32_e32 v17, v16
	v_exp_f32_e32 v20, v18
	v_exp_f32_e32 v21, v36
	v_exp_f32_e32 v16, v22
	v_sub_f32_e32 v8, v8, v33
	v_sub_f32_e32 v24, v24, v33
	v_sub_f32_e32 v39, v25, v33
	v_sub_f32_e32 v10, v10, v33
	v_sub_f32_e32 v26, v26, v33
	v_sub_f32_e32 v25, v11, v33
	v_exp_f32_e32 v3, v32
	v_exp_f32_e32 v11, v23
	v_exp_f32_e32 v19, v34
	v_exp_f32_e32 v18, v35
	v_exp_f32_e32 v23, v37
	v_exp_f32_e32 v22, v38
	v_sub_f32_e32 v40, v27, v33
	v_sub_f32_e32 v27, v13, v33
	v_exp_f32_e32 v9, v8
	v_exp_f32_e32 v8, v10
	v_exp_f32_e32 v10, v25
	v_exp_f32_e32 v25, v24
	v_exp_f32_e32 v24, v26
	s_lshl_b32 s4, s66, 2
	v_sub_f32_e32 v12, v12, v33
	v_sub_f32_e32 v28, v28, v33
	v_sub_f32_e32 v41, v29, v33
	v_sub_f32_e32 v14, v14, v33
	v_sub_f32_e32 v30, v30, v33
	v_sub_f32_e32 v29, v15, v33
	v_exp_f32_e32 v15, v27
	v_exp_f32_e32 v27, v39
	v_exp_f32_e32 v26, v40
	s_add_i32 s66, s4, 4
	v_sub_f32_e32 v42, v31, v33
	v_exp_f32_e32 v13, v12
	v_exp_f32_e32 v12, v14
	v_exp_f32_e32 v14, v29
	v_exp_f32_e32 v29, v28
	v_exp_f32_e32 v28, v30
	v_pk_add_f32 v[36:37], v[4:5], v[20:21]
	v_pk_add_f32 v[38:39], v[0:1], v[16:17]
	s_xor_b32 s67, s4, -3
	v_readlane_b32 s4, v254, 39
	v_exp_f32_e32 v31, v41
	v_exp_f32_e32 v30, v42
	v_pk_add_f32 v[34:35], v[2:3], v[18:19]
	v_pk_add_f32 v[36:37], v[36:37], v[38:39]
	v_pk_add_f32 v[38:39], v[6:7], v[22:23]
	s_add_i32 s4, s4, s65
	v_pk_add_f32 v[34:35], v[34:35], v[38:39]
	v_pk_add_f32 v[38:39], v[8:9], v[24:25]
	v_cvt_pk_bf16_f32 v143, v0, v6
	v_add_u32_e32 v0, s4, v161
	s_add_u32 s4, s74, s72
	v_pk_add_f32 v[36:37], v[38:39], v[36:37]
	v_pk_add_f32 v[38:39], v[10:11], v[26:27]
	s_addc_u32 s5, 0, s73
	s_lshl_b32 s7, s33, 7
	v_mov_b32_e32 v147, v153
	v_pk_add_f32 v[34:35], v[38:39], v[34:35]
	v_pk_add_f32 v[38:39], v[12:13], v[28:29]
	s_lshl_b32 s6, s64, 7
	s_and_b32 s7, s7, 0x700
	v_pk_add_f32 v[36:37], v[38:39], v[36:37]
	v_pk_add_f32 v[38:39], v[14:15], v[30:31]
	v_cvt_pk_bf16_f32 v140, v1, v3
	v_sub_u32_e32 v173, v0, v166
	v_lshl_add_u64 v[0:1], s[4:5], 0, v[146:147]
	s_or_b32 s8, s7, s6
	v_readlane_b32 s6, v254, 41
	v_pk_add_f32 v[34:35], v[38:39], v[34:35]
	v_cvt_pk_bf16_f32 v141, v4, v2
	v_lshlrev_b64 v[0:1], 12, v[0:1]
	v_and_b32_e32 v2, 3, v58
	s_add_u32 s6, s6, s8
	v_readlane_b32 s7, v254, 42
	v_pk_add_f32 v[34:35], v[34:35], v[36:37]
	v_lshl_or_b32 v0, v2, 4, v0
	s_addc_u32 s7, s7, 0
	v_pk_add_f32 v[34:35], v[34:35], v[34:35] op_sel:[0,1] op_sel_hi:[1,0]
	v_lshl_add_u64 v[154:155], s[6:7], 0, v[0:1]
	v_lshl_add_u64 v[0:1], s[4:5], 0, v[152:153]
	v_mov_b32_e32 v32, v34
	v_lshlrev_b64 v[2:3], 6, v[0:1]
	v_readlane_b32 s4, v254, 43
	v_lshlrev_b32_e32 v169, 3, v59
	v_permlane32_swap_b32_e32 v34, v32
	v_and_or_b32 v2, v58, 48, v2
	v_readlane_b32 s5, v254, 44
	v_lshlrev_b64 v[0:1], 12, v[0:1]
	v_add_f32_e32 v32, v34, v32
	v_lshl_add_u64 v[156:157], s[4:5], 0, v[2:3]
	v_or_b32_e32 v0, s8, v0
	v_add_lshl_u32 v2, s90, v169, 1
	v_mov_b32_e32 v3, v153
	v_readlane_b32 s4, v254, 45
	v_pk_add_f32 v[150:151], v[32:33], 0 op_sel_hi:[1,0]
	v_cvt_pk_bf16_f32 v138, v13, v15
	v_cvt_pk_bf16_f32 v139, v12, v14
	v_lshl_add_u64 v[0:1], v[0:1], 0, v[2:3]
	v_readlane_b32 s5, v254, 46
	v_mov_b32_e32 v14, v153
	v_mov_b32_e32 v15, v153
	v_and_b32_e32 v167, 63, v58
	v_xor_b32_e32 v32, 0x80000000, v151
	v_cvt_pk_bf16_f32 v142, v5, v7
	v_cvt_pk_bf16_f32 v136, v9, v11
	v_cvt_pk_bf16_f32 v137, v8, v10
	v_cvt_pk_bf16_f32 v132, v17, v19
	v_cvt_pk_bf16_f32 v133, v20, v18
	v_cvt_pk_bf16_f32 v134, v21, v23
	v_cvt_pk_bf16_f32 v135, v16, v22
	v_cvt_pk_bf16_f32 v128, v25, v27
	v_cvt_pk_bf16_f32 v129, v24, v26
	v_cvt_pk_bf16_f32 v130, v29, v31
	v_cvt_pk_bf16_f32 v131, v28, v30
	v_lshl_add_u64 v[158:159], s[4:5], 0, v[0:1]
	v_mov_b32_e32 v0, v153
	v_mov_b32_e32 v1, v153
	v_mov_b32_e32 v2, v153
	v_mov_b32_e32 v4, v153
	v_mov_b32_e32 v5, v153
	v_mov_b32_e32 v6, v153
	v_mov_b32_e32 v7, v153
	v_mov_b32_e32 v8, v153
	v_mov_b32_e32 v9, v153
	v_mov_b32_e32 v10, v153
	v_mov_b32_e32 v11, v153
	v_mov_b32_e32 v12, v153
	v_mov_b32_e32 v13, v153
	v_mov_b64_e32 v[30:31], v[14:15]
	v_lshlrev_b32_e32 v170, 3, v60
	s_mov_b32 s85, 4
	v_cmp_gt_u32_e64 s[2:3], 32, v167
	v_lshl_add_u32 v171, v161, 2, s89
	v_lshl_add_u32 v168, v166, 2, s89
	s_mov_b32 s82, 1
	s_mov_b32 s68, 0
	s_movk_i32 s33, 0x7f
	v_mov_b64_e32 v[28:29], v[12:13]
	v_mov_b64_e32 v[26:27], v[10:11]
	v_mov_b64_e32 v[24:25], v[8:9]
	v_mov_b64_e32 v[22:23], v[6:7]
	v_mov_b64_e32 v[20:21], v[4:5]
	v_mov_b64_e32 v[18:19], v[2:3]
	v_mov_b64_e32 v[16:17], v[0:1]
	v_mov_b32_e32 v33, v32
	v_mov_b32_e32 v34, v32
	v_mov_b32_e32 v35, v32
	v_mov_b32_e32 v36, v32
	v_mov_b32_e32 v37, v32
	v_mov_b32_e32 v38, v32
	v_mov_b32_e32 v39, v32
	v_mov_b32_e32 v40, v32
	v_mov_b32_e32 v41, v32
	v_mov_b32_e32 v42, v32
	v_mov_b32_e32 v43, v32
	v_mov_b32_e32 v44, v32
	v_mov_b32_e32 v45, v32
	v_mov_b32_e32 v46, v32
	v_mov_b32_e32 v47, v32
	v_mul_f32_e32 v150, 0.5, v150
	v_add_u32_e32 v173, s33, v173

.LBB0_1418:
	v_exp_f32_e32 v190, v64
	v_exp_f32_e32 v194, v68
	v_exp_f32_e32 v174, v48
	v_exp_f32_e32 v178, v52
	v_exp_f32_e32 v191, v65
	v_exp_f32_e32 v195, v69
	v_exp_f32_e32 v175, v49
	v_exp_f32_e32 v179, v53
	v_exp_f32_e32 v192, v66
	v_exp_f32_e32 v196, v70
	v_exp_f32_e32 v176, v50
	v_exp_f32_e32 v180, v54
	v_exp_f32_e32 v193, v67
	v_exp_f32_e32 v197, v71
	v_exp_f32_e32 v177, v51
	v_exp_f32_e32 v181, v55
	v_exp_f32_e32 v198, v72
	v_exp_f32_e32 v182, v56
	v_add_f32_e32 v96, v174, v190
	v_add_f32_e32 v100, v178, v194
	v_exp_f32_e32 v199, v73
	v_exp_f32_e32 v183, v57
	v_add_f32_e32 v97, v175, v191
	v_add_f32_e32 v96, v96, v100
	v_add_f32_e32 v100, v179, v195
	v_exp_f32_e32 v200, v74
	v_exp_f32_e32 v184, v58
	v_add_f32_e32 v98, v176, v192
	v_add_f32_e32 v97, v97, v100
	v_add_f32_e32 v100, v180, v196
	v_exp_f32_e32 v201, v75
	v_exp_f32_e32 v185, v59
	v_add_f32_e32 v99, v177, v193
	v_add_f32_e32 v98, v98, v100
	v_add_f32_e32 v100, v181, v197
	v_exp_f32_e32 v202, v76
	v_exp_f32_e32 v186, v60
	v_add_f32_e32 v99, v99, v100
	v_add_f32_e32 v100, v182, v198
	v_exp_f32_e32 v203, v77
	v_exp_f32_e32 v187, v61
	v_add_f32_e32 v96, v100, v96
	v_add_f32_e32 v100, v183, v199
	v_exp_f32_e32 v204, v78
	v_exp_f32_e32 v188, v62
	v_add_f32_e32 v97, v100, v97
	v_add_f32_e32 v100, v184, v200
	v_exp_f32_e32 v205, v79
	v_exp_f32_e32 v189, v63
	v_add_f32_e32 v98, v100, v98
	v_add_f32_e32 v100, v185, v201
	v_add_f32_e32 v99, v100, v99
	v_add_f32_e32 v100, v186, v202
	v_add_f32_e32 v96, v100, v96
	v_add_f32_e32 v100, v187, v203
	v_add_f32_e32 v97, v100, v97
	v_add_f32_e32 v100, v188, v204
	v_add_f32_e32 v98, v100, v98
	v_add_f32_e32 v100, v189, v205
	v_add_f32_e32 v99, v100, v99
	v_add_f32_e32 v96, v96, v97
	v_add_f32_e32 v97, v98, v99
	v_add_f32_e32 v96, v96, v97
	v_cmp_le_f32_e32 vcc, 0x43700000, v96
	v_cvt_pk_bf16_f32 v140, v190, v191
	v_cvt_pk_bf16_f32 v141, v192, v193
	s_cbranch_vccnz .Lat_slow

; #define SBAR() __builtin_amdgcn_sched_barrier(0)
; #define DMA_K(t, slot) do { if constexpr ((VAR & 16) != 0) break; __builtin_amdgcn_global_load_lds((const unsigned*)(ksrc + (size_t)TT(t) * 64 * KVW), (LAS unsigned*)(kdst + (slot) * KSLOT), 16, 0, 0); \
;                             __builtin_amdgcn_global_load_lds((const unsigned*)(rsrc + (size_t)TT(t) * 64 * ROPE), (LAS unsigned*)(rdst + (slot) * KSLOT), 16, 0, 0); } while (0)
; #define DMA_V(t, slot) do { if constexpr ((VAR & 16) == 0) __builtin_amdgcn_global_load_lds((const unsigned*)(vsrc + (size_t)TT(t) * 64 * KVW), (LAS unsigned*)(vdst + (slot) * VSLOT), 16, 0, 0); } while (0)
; #define KLOAD(slot) do { const LAS unsigned char* kb_ = kb0 + (slot) * KSLOT; _Pragma("unroll") for (int d0 = 0; d0 < 6; ++d0) { kf[2 * d0] = *(const LAS bf16x8*)(kb_ + d0 * 512); kf[2 * d0 + 1] = *(const LAS bf16x8*)(kb_ + d0 * 512 + 6144); } } while (0)
; #define RESC(al) do { if (__any((al) < 1.f)) { if (hi == 0) al_l[r32] = (al); asm volatile("s_waitcnt lgkmcnt(0)" ::: "memory"); \
;         _Pragma("unroll") for (int d_ = 0; d_ < 2; ++d_) _Pragma("unroll") for (int r = 0; r < 16; ++r) o[d_][r] *= al_l[crow(r, hi)]; } } while (0)
; #define MASKT(P0_, P1_, t) do { const int kbm_ = TT(t) * 64; if (kbm_ + 63 > qlo) mask_tile(P0_, P1_, qm - kbm_); } while (0)
; #define PBAR_M(t) do { if ((t) + 3 < NT) { WAIT_BAR(6); } else { WAIT_BAR(0); } } while (0)
; template <int VAR> __device__ __forceinline__ void block(const bf16* Q, const bf16* KVB, const bf16* KR, const float* cosT, bf16* OB, LAS unsigned char* lds, int b, int h, int qb, int t0, int wv, ...
;     ...
;     for (int t = 1; t < NT; ++t) {
;         PBAR_M(t);
;         { if (t + 3 < NT) DMA_K(t + 3, (sk + 3) & 3); if (t + 2 < NT) DMA_V(t + 2, (sk + 2) & 3); }
;         SBAR();
;         KLOAD(sk); VREAD(sv);
;         SBAR();
;         QK(px0, px1);
;         SBAR(); asm volatile("s_waitcnt lgkmcnt(0)" ::: "memory"); SBAR();
;         PVALL();
;         PBAR_V(t);
;         MASKT(px0, px1, t);
;         float pm_, alX = 1.f; ROWMAX(px0, px1, pm_);
;         if (__builtin_expect(__any(pm_ > THR), 0)) { const float dl_ = fmaxf(pm_, 0.f); SHIFT(px0, px1, dl_); alX = __builtin_amdgcn_exp2f(-dl_); }
;         TILE_VALU(alX);
;         pa0 = pn0; pa1 = pn1; pa2 = pn2; pa3 = pn3;
;         RESC(alX);
;         sk = (sk + 1) & 3; sv = (sv + 1) & 3;
.LBB0_1422:
	s_add_i32 s4, s82, 1
	s_and_b32 s82, s4, 3
	s_add_i32 s4, s68, 1
	s_add_i32 s85, s85, 1
	s_and_b32 s68, s4, 3
	s_add_i32 s4, s67, s85
	s_add_i32 s33, s33, 64
	v_lshl_add_u64 v[154:155], v[154:155], 0, s[94:95]
	v_lshl_add_u64 v[156:157], v[156:157], 0, s[70:71]
	v_lshl_add_u64 v[158:159], v[158:159], 0, s[94:95]
	v_cvt_pk_bf16_f32 v142, v194, v195
	v_cvt_pk_bf16_f32 v143, v196, v197
	v_cvt_pk_bf16_f32 v136, v198, v199
	v_cvt_pk_bf16_f32 v137, v200, v201
	v_cvt_pk_bf16_f32 v138, v202, v203
	v_cvt_pk_bf16_f32 v139, v204, v205
	v_cvt_pk_bf16_f32 v132, v174, v175
	v_cvt_pk_bf16_f32 v133, v176, v177
	v_cvt_pk_bf16_f32 v134, v178, v179
	v_cvt_pk_bf16_f32 v135, v180, v181
	v_cvt_pk_bf16_f32 v128, v182, v183
	v_cvt_pk_bf16_f32 v129, v184, v185
	v_cvt_pk_bf16_f32 v130, v186, v187
	v_cvt_pk_bf16_f32 v131, v188, v189
	s_cmp_eq_u32 s4, 4
	s_cbranch_scc1 .LBB0_1430
	s_cmp_ge_u32 s85, s66
	s_cselect_b64 s[4:5], -1, 0
	s_cbranch_scc1 .Lat_mbar0
	s_waitcnt vmcnt(6) lgkmcnt(0)
	s_barrier
	s_branch .Lat_mreads

; __device__ __forceinline__ void mask_tile(f32x16& p0, f32x16& p1, int dq) {
;     const float NEG = -__builtin_inff();
; #pragma unroll
;     for (int r = 0; r < 16; ++r) { const int c = (r & 3) + 8 * (r >> 2); if (dq - c < 0) p0[r] = NEG; if (dq - c - 32 < 0) p1[r] = NEG; }
; }
.LBB0_1416:
	v_subrev_u32_e32 v101, s33, v173
	v_cmp_gt_i32_e64 s[62:63], 26, v101
	v_cmp_gt_i32_e64 s[64:65], 27, v101
	v_cmp_gt_i32_e64 s[60:61], 25, v101
	s_and_b64 s[62:63], s[64:65], s[62:63]
	v_cmp_gt_i32_e64 s[58:59], 24, v101
	s_and_b64 s[60:61], s[62:63], s[60:61]
	v_cmp_gt_i32_e64 s[56:57], 19, v101
	s_and_b64 s[58:59], s[60:61], s[58:59]
	v_cmp_gt_i32_e64 s[54:55], 18, v101
	s_and_b64 s[56:57], s[58:59], s[56:57]
	v_cmp_gt_i32_e64 s[52:53], 17, v101
	s_and_b64 s[54:55], s[56:57], s[54:55]
	v_cmp_gt_i32_e64 s[50:51], 16, v101
	s_and_b64 s[52:53], s[54:55], s[52:53]
	v_cmp_gt_i32_e64 s[48:49], 11, v101
	s_and_b64 s[50:51], s[52:53], s[50:51]
	v_cmp_gt_i32_e64 s[46:47], 10, v101
	s_and_b64 s[48:49], s[50:51], s[48:49]
	v_cmp_gt_i32_e64 s[44:45], 9, v101
	s_and_b64 s[46:47], s[48:49], s[46:47]
	v_cmp_gt_i32_e64 s[42:43], 8, v101
	s_and_b64 s[44:45], s[46:47], s[44:45]
	v_cmp_gt_i32_e64 s[40:41], 3, v101
	s_and_b64 s[42:43], s[44:45], s[42:43]
	v_cmp_gt_i32_e64 s[38:39], 2, v101
	s_and_b64 s[40:41], s[42:43], s[40:41]
	v_cmp_gt_i32_e64 s[36:37], 1, v101
	s_and_b64 s[38:39], s[40:41], s[38:39]
	v_cmp_gt_i32_e64 s[34:35], 0, v101
	s_and_b64 s[36:37], s[38:39], s[36:37]
	s_and_b64 s[34:35], s[36:37], s[34:35]
	v_cmp_gt_i32_e64 s[30:31], 58, v101
	v_cndmask_b32_e64 v64, v64, v164, s[34:35]
	v_cmp_gt_i32_e64 s[34:35], 59, v101
	v_cmp_gt_i32_e64 s[28:29], 57, v101
	s_and_b64 s[30:31], s[34:35], s[30:31]
	v_cmp_gt_i32_e64 s[26:27], 56, v101
	s_and_b64 s[28:29], s[30:31], s[28:29]
	v_cmp_gt_i32_e64 s[24:25], 51, v101
	s_and_b64 s[26:27], s[28:29], s[26:27]
	v_cmp_gt_i32_e64 s[22:23], 50, v101
	s_and_b64 s[24:25], s[26:27], s[24:25]
	v_cmp_gt_i32_e64 s[20:21], 49, v101
	s_and_b64 s[22:23], s[24:25], s[22:23]
	v_cmp_gt_i32_e64 s[18:19], 48, v101
	s_and_b64 s[20:21], s[22:23], s[20:21]
	v_cmp_gt_i32_e64 s[16:17], 43, v101
	s_and_b64 s[18:19], s[20:21], s[18:19]
	v_cmp_gt_i32_e64 s[14:15], 42, v101
	s_and_b64 s[16:17], s[18:19], s[16:17]
	v_cmp_gt_i32_e64 s[12:13], 41, v101
	s_and_b64 s[14:15], s[16:17], s[14:15]
	v_cmp_gt_i32_e64 s[10:11], 40, v101
	s_and_b64 s[12:13], s[14:15], s[12:13]
	v_cmp_gt_i32_e64 s[8:9], 35, v101
	s_and_b64 s[10:11], s[12:13], s[10:11]
	v_cmp_gt_i32_e64 s[6:7], 34, v101
	s_and_b64 s[8:9], s[10:11], s[8:9]
	v_cmp_gt_i32_e64 s[4:5], 33, v101
	s_and_b64 s[6:7], s[8:9], s[6:7]
	v_cmp_gt_i32_e32 vcc, 32, v101
	s_and_b64 s[4:5], s[6:7], s[4:5]
	s_and_b64 vcc, s[4:5], vcc
	v_cndmask_b32_e64 v79, v79, v164, s[64:65]
	v_cndmask_b32_e64 v78, v78, v164, s[62:63]
	v_cndmask_b32_e64 v77, v77, v164, s[60:61]
	v_cndmask_b32_e64 v76, v76, v164, s[58:59]
	v_cndmask_b32_e64 v75, v75, v164, s[56:57]
	v_cndmask_b32_e64 v74, v74, v164, s[54:55]
	v_cndmask_b32_e64 v73, v73, v164, s[52:53]
	v_cndmask_b32_e64 v72, v72, v164, s[50:51]
	v_cndmask_b32_e64 v71, v71, v164, s[48:49]
	v_cndmask_b32_e64 v70, v70, v164, s[46:47]
	v_cndmask_b32_e64 v69, v69, v164, s[44:45]
	v_cndmask_b32_e64 v68, v68, v164, s[42:43]
	v_cndmask_b32_e64 v67, v67, v164, s[40:41]
	v_cndmask_b32_e64 v66, v66, v164, s[38:39]
	v_cndmask_b32_e64 v65, v65, v164, s[36:37]
	v_cndmask_b32_e64 v63, v63, v164, s[34:35]
	v_cndmask_b32_e64 v62, v62, v164, s[30:31]
	v_cndmask_b32_e64 v61, v61, v164, s[28:29]
	v_cndmask_b32_e64 v60, v60, v164, s[26:27]
	v_cndmask_b32_e64 v59, v59, v164, s[24:25]
	v_cndmask_b32_e64 v58, v58, v164, s[22:23]
	v_cndmask_b32_e64 v57, v57, v164, s[20:21]
	v_cndmask_b32_e64 v56, v56, v164, s[18:19]
	v_cndmask_b32_e64 v55, v55, v164, s[16:17]
	v_cndmask_b32_e64 v54, v54, v164, s[14:15]
	v_cndmask_b32_e64 v53, v53, v164, s[12:13]
	v_cndmask_b32_e64 v52, v52, v164, s[10:11]
	v_cndmask_b32_e64 v51, v51, v164, s[8:9]
	v_cndmask_b32_e64 v50, v50, v164, s[6:7]
	v_cndmask_b32_e64 v49, v49, v164, s[4:5]
	v_cndmask_b32_e32 v48, v48, v164, vcc
	s_branch .LBB0_1418

.Lat_sexp:
	v_exp_f32_e32 v190, v64
	v_exp_f32_e32 v194, v68
	v_exp_f32_e32 v174, v48
	v_exp_f32_e32 v178, v52
	v_exp_f32_e32 v191, v65
	v_exp_f32_e32 v195, v69
	v_exp_f32_e32 v175, v49
	v_exp_f32_e32 v179, v53
	v_exp_f32_e32 v192, v66
	v_exp_f32_e32 v196, v70
	v_exp_f32_e32 v176, v50
	v_exp_f32_e32 v180, v54
	v_exp_f32_e32 v193, v67
	v_exp_f32_e32 v197, v71
	v_exp_f32_e32 v177, v51
	v_exp_f32_e32 v181, v55
	v_exp_f32_e32 v198, v72
	v_exp_f32_e32 v182, v56
	v_add_f32_e32 v96, v174, v190
	v_add_f32_e32 v100, v178, v194
	v_exp_f32_e32 v199, v73
	v_exp_f32_e32 v183, v57
	v_add_f32_e32 v97, v175, v191
	v_add_f32_e32 v96, v96, v100
	v_add_f32_e32 v100, v179, v195
	v_exp_f32_e32 v200, v74
	v_exp_f32_e32 v184, v58
	v_add_f32_e32 v98, v176, v192
	v_add_f32_e32 v97, v97, v100
	v_add_f32_e32 v100, v180, v196
	v_exp_f32_e32 v201, v75
	v_exp_f32_e32 v185, v59
	v_add_f32_e32 v99, v177, v193
	v_add_f32_e32 v98, v98, v100
	v_add_f32_e32 v100, v181, v197
	v_exp_f32_e32 v202, v76
	v_exp_f32_e32 v186, v60
	v_add_f32_e32 v99, v99, v100
	v_add_f32_e32 v100, v182, v198
	v_exp_f32_e32 v203, v77
	v_exp_f32_e32 v187, v61
	v_add_f32_e32 v96, v100, v96
	v_add_f32_e32 v100, v183, v199
	v_exp_f32_e32 v204, v78
	v_exp_f32_e32 v188, v62
	v_add_f32_e32 v97, v100, v97
	v_add_f32_e32 v100, v184, v200
	v_exp_f32_e32 v205, v79
	v_exp_f32_e32 v189, v63
	v_add_f32_e32 v98, v100, v98
	v_add_f32_e32 v100, v185, v201
	v_add_f32_e32 v99, v100, v99
	v_add_f32_e32 v100, v186, v202
	v_add_f32_e32 v96, v100, v96
	v_add_f32_e32 v100, v187, v203
	v_add_f32_e32 v97, v100, v97
	v_add_f32_e32 v100, v188, v204
	v_add_f32_e32 v98, v100, v98
	v_add_f32_e32 v100, v189, v205
	v_add_f32_e32 v99, v100, v99
	v_add_f32_e32 v96, v96, v97
	v_add_f32_e32 v97, v98, v99
	v_add_f32_e32 v96, v96, v97
	v_cvt_pk_bf16_f32 v140, v190, v191
	v_cvt_pk_bf16_f32 v141, v192, v193
	s_cmp_lg_u32 s5, 0
	s_cbranch_scc1 .Lat_resc
	s_branch .Lat_vjoin

; #define LAS __attribute__((address_space(3)))
; __device__ __forceinline__ bf16 f2bf(float f) { return (bf16)(pk2(f, 0.f) & 0xffffu); }
; __device__ __forceinline__ int crow(int r, int hi) { return (r & 3) + 8 * (r >> 2) + 4 * hi; }
; template <int VAR> __device__ __forceinline__ void block(const bf16* Q, const bf16* KVB, const bf16* KR, const float* cosT, bf16* OB, LAS unsigned char* lds, int b, int h, int qb, int t0, int wv, ...
;     ...
;     if (hi == 0) li_l[r32] = l_reg; asm volatile("s_waitcnt lgkmcnt(0)" ::: "memory");
;     bf16* Ow = OB + (rowbase + P0 + wid * 32) * DM + h * 64;
;     {
;         LAS bf16* stg = (LAS bf16*)(lds + LDS_OST) + wid * 2048;
; #pragma unroll
;         for (int r = 0; r < 16; ++r) { const int orow = crow(r, hi); const float rl = __builtin_amdgcn_rcpf(li_l[orow]);
; #pragma unroll
;             for (int d0 = 0; d0 < 2; ++d0) stg[orow * 64 + d0 * 32 + r32] = f2bf(o[d0][r] * rl); }
;         asm volatile("s_waitcnt lgkmcnt(0)" ::: "memory");
; #pragma unroll
;         for (int i4 = 0; i4 < 4; ++i4) { const int row = i4 * 8 + (lane >> 3), ch = lane & 7; const u32x4 v = *(const LAS u32x4*)(stg + row * 64 + ch * 8); *(u32x4*)(Ow + (size_t)row * DM + ch * 8) = v; }
;     }
.LBB0_1434:
	v_mov_b32_e32 v97, v150
	s_nop 1
	v_permlane32_swap_b32_e32 v150, v97
	v_add_f32_e32 v150, v150, v97
	s_and_saveexec_b64 s[8:9], s[2:3]
	ds_write_b32 v171, v150
	s_or_b64 exec, exec, s[8:9]
	s_waitcnt lgkmcnt(0)
	ds_read_b128 v[32:35], v168
	ds_read_b128 v[36:39], v168 offset:32
	v_lshl_add_u32 v40, v161, 1, s97
	v_lshl_add_u32 v41, v162, 9, v40
	s_add_u32 s2, s72, s77
	s_waitcnt lgkmcnt(0)
	v_rcp_f32_e32 v32, v32
	s_addc_u32 s3, 0, s73
	s_lshl_b64 s[2:3], s[2:3], 11
	v_readlane_b32 s8, v254, 20
	v_mul_f32_e32 v16, v16, v32
	v_cvt_pk_bf16_f32 v16, v16, s0
	ds_write_b16 v41, v16
	v_rcp_f32_e32 v16, v33
	v_mul_f32_e32 v0, v0, v32
	v_cvt_pk_bf16_f32 v0, v0, s0
	ds_write_b16 v41, v0 offset:64
	v_mul_f32_e32 v0, v17, v16
	v_cvt_pk_bf16_f32 v0, v0, s0
	v_lshl_add_u32 v32, v166, 7, v40
	ds_write_b16 v32, v0 offset:128
	v_rcp_f32_e32 v0, v34
	v_mul_f32_e32 v1, v1, v16
	v_cvt_pk_bf16_f32 v1, v1, s0
	ds_write_b16 v32, v1 offset:192
	v_mul_f32_e32 v1, v18, v0
	v_cvt_pk_bf16_f32 v1, v1, s0
	ds_write_b16 v32, v1 offset:256
	v_rcp_f32_e32 v1, v35
	v_mul_f32_e32 v0, v2, v0
	v_cvt_pk_bf16_f32 v0, v0, s0
	ds_write_b16 v32, v0 offset:320
	v_mul_f32_e32 v0, v19, v1
	v_cvt_pk_bf16_f32 v0, v0, s0
	ds_write_b16 v32, v0 offset:384
	v_rcp_f32_e32 v0, v36
	v_mul_f32_e32 v1, v3, v1
	v_cvt_pk_bf16_f32 v1, v1, s0
	ds_write_b16 v32, v1 offset:448
	v_mul_f32_e32 v1, v20, v0
	v_cvt_pk_bf16_f32 v1, v1, s0
	ds_write_b16 v32, v1 offset:1024
	v_rcp_f32_e32 v1, v37
	v_mul_f32_e32 v0, v4, v0
	v_cvt_pk_bf16_f32 v0, v0, s0
	ds_write_b16 v32, v0 offset:1088
	v_mul_f32_e32 v0, v21, v1
	v_cvt_pk_bf16_f32 v0, v0, s0
	ds_write_b16 v32, v0 offset:1152
	v_rcp_f32_e32 v0, v38
	v_mul_f32_e32 v1, v5, v1
	v_cvt_pk_bf16_f32 v1, v1, s0
	ds_write_b16 v32, v1 offset:1216
	v_mul_f32_e32 v1, v22, v0
	v_mul_f32_e32 v0, v6, v0
	v_cvt_pk_bf16_f32 v1, v1, s0
	v_cvt_pk_bf16_f32 v0, v0, s0
	ds_write_b16 v32, v1 offset:1280
	ds_write_b16 v32, v0 offset:1344
	ds_read_b128 v[0:3], v168 offset:64
	ds_read_b128 v[16:19], v168 offset:96
	v_rcp_f32_e32 v4, v39
	s_add_u32 s2, s8, s2
	v_readlane_b32 s8, v254, 21
	s_waitcnt lgkmcnt(0)
	v_rcp_f32_e32 v0, v0
	v_mul_f32_e32 v5, v23, v4
	v_mul_f32_e32 v4, v7, v4
	v_rcp_f32_e32 v1, v1
	v_cvt_pk_bf16_f32 v4, v4, s0
	ds_write_b16 v32, v4 offset:1472
	v_mul_f32_e32 v4, v24, v0
	v_mul_f32_e32 v0, v8, v0
	v_cvt_pk_bf16_f32 v0, v0, s0
	ds_write_b16 v32, v0 offset:2112
	v_mul_f32_e32 v0, v25, v1
	v_cvt_pk_bf16_f32 v0, v0, s0
	ds_write_b16 v32, v0 offset:2176
	v_rcp_f32_e32 v0, v2
	v_mul_f32_e32 v1, v9, v1
	v_cvt_pk_bf16_f32 v1, v1, s0
	ds_write_b16 v32, v1 offset:2240
	v_mul_f32_e32 v1, v26, v0
	v_cvt_pk_bf16_f32 v1, v1, s0
	ds_write_b16 v32, v1 offset:2304
	v_rcp_f32_e32 v1, v3
	v_mul_f32_e32 v0, v10, v0
	v_cvt_pk_bf16_f32 v0, v0, s0
	ds_write_b16 v32, v0 offset:2368
	v_mul_f32_e32 v0, v27, v1
	v_cvt_pk_bf16_f32 v0, v0, s0
	ds_write_b16 v32, v0 offset:2432
	v_rcp_f32_e32 v0, v16
	v_mul_f32_e32 v1, v11, v1
	v_cvt_pk_bf16_f32 v1, v1, s0
	ds_write_b16 v32, v1 offset:2496
	v_mul_f32_e32 v1, v28, v0
	v_cvt_pk_bf16_f32 v1, v1, s0
	ds_write_b16 v32, v1 offset:3072
	v_rcp_f32_e32 v1, v17
	v_mul_f32_e32 v0, v12, v0
	v_cvt_pk_bf16_f32 v0, v0, s0
	ds_write_b16 v32, v0 offset:3136
	v_mul_f32_e32 v0, v29, v1
	v_cvt_pk_bf16_f32 v0, v0, s0
	ds_write_b16 v32, v0 offset:3200
	v_rcp_f32_e32 v0, v18
	v_mul_f32_e32 v1, v13, v1
	v_cvt_pk_bf16_f32 v1, v1, s0
	ds_write_b16 v32, v1 offset:3264
	v_mul_f32_e32 v1, v30, v0
	v_cvt_pk_bf16_f32 v1, v1, s0
	ds_write_b16 v32, v1 offset:3328
	v_rcp_f32_e32 v1, v19
	v_mul_f32_e32 v0, v14, v0
	v_cvt_pk_bf16_f32 v0, v0, s0
	ds_write_b16 v32, v0 offset:3392
	v_mul_f32_e32 v0, v31, v1
	v_cvt_pk_bf16_f32 v0, v0, s0
	ds_write_b16 v32, v0 offset:3456
	v_mul_f32_e32 v0, v15, v1
	v_cvt_pk_bf16_f32 v0, v0, s0
	ds_write_b16 v32, v0 offset:3520
	v_lshlrev_b32_e32 v0, 1, v160
	v_cvt_pk_bf16_f32 v5, v5, s0
	v_cvt_pk_bf16_f32 v4, v4, s0
	v_and_b32_e32 v152, 0x70, v0
	ds_write_b16 v32, v5 offset:1408
	ds_write_b16 v32, v4 offset:2048
	v_lshrrev_b32_e32 v12, 3, v167
	v_add_u32_e32 v13, s97, v152
	s_waitcnt lgkmcnt(0)
	v_lshl_add_u32 v0, v12, 7, v13
	v_or_b32_e32 v14, 8, v12
	s_addc_u32 s3, s8, s3
	s_lshl_b32 s8, s86, 1
	ds_read_b128 v[0:3], v0
	v_lshl_add_u32 v4, v14, 7, v13
	s_add_u32 s2, s2, s8
	ds_read_b128 v[4:7], v4
	s_addc_u32 s3, s3, 0
	v_lshl_add_u64 v[8:9], s[2:3], 0, v[152:153]
	v_lshlrev_b32_e32 v152, 11, v12
	v_lshl_add_u64 v[10:11], v[8:9], 0, v[152:153]
	v_lshlrev_b32_e32 v152, 11, v14
	s_waitcnt lgkmcnt(0)
	global_store_dwordx4 v[10:11], v[0:3], off
	s_andn2_b64 vcc, exec, s[4:5]
	s_nop 0
	v_lshl_add_u64 v[0:1], v[8:9], 0, v[152:153]
	global_store_dwordx4 v[0:1], v[4:7], off
	s_nop 1
	v_or_b32_e32 v4, 16, v12
	v_lshl_add_u32 v0, v4, 7, v13
	v_or_b32_e32 v12, 24, v12
	ds_read_b128 v[0:3], v0
	v_lshlrev_b32_e32 v152, 11, v4
	v_lshl_add_u32 v4, v12, 7, v13
	ds_read_b128 v[4:7], v4
	v_lshl_add_u64 v[10:11], v[8:9], 0, v[152:153]
	v_lshlrev_b32_e32 v152, 11, v12
	s_waitcnt lgkmcnt(0)
	global_store_dwordx4 v[10:11], v[0:3], off
	s_nop 1
	v_lshl_add_u64 v[0:1], v[8:9], 0, v[152:153]
	global_store_dwordx4 v[0:1], v[4:7], off
	s_cbranch_vccz .LBB0_1439
	s_andn2_b64 vcc, exec, s[6:7]
	s_mov_b32 s6, s76
	s_cbranch_vccz .LBB0_1440
